# one-time cooperative grid.sync replaced by the kernel's own xcd barrier path; on top of epilogue/attention-setup load batching
# speedup vs baseline: 1.0057x; 1.0057x over previous
; #define GAS __attribute__((address_space(1)))
; __device__ __forceinline__ void xcd_barrier(const XcdBarrier& b) {
;     asm volatile("s_waitcnt vmcnt(0)" ::: "memory");
;     __syncthreads();
;     if (threadIdx.x == 0) {
;         GAS unsigned* bar = b.bar;
;         __builtin_amdgcn_s_waitcnt(0);
;         unsigned nloc = b.st[0], nx = b.st[1];
;         if (nloc == 0u) { xcd_barrier_complete(bar, b.x, nloc, nx); b.st[0] = nloc; b.st[1] = nx; }
.LBB0_84:
	v_readlane_b32 s0, v254, 33
	s_or_b32 s33, s0, 1
	s_cmp_lt_i32 s33, s69
	s_cselect_b64 s[0:1], -1, 0
	s_and_b64 s[2:3], s[2:3], s[0:1]
	s_andn2_b64 vcc, exec, s[2:3]
	s_cbranch_vccnz .LBB0_152
	s_cmp_lg_u32 s28, 0
	v_readlane_b32 s2, v254, 32
	s_nop 1
	v_mov_b32_e32 v0, s2
	s_waitcnt lgkmcnt(0)
	ds_read_b64 v[2:3], v0 offset:136
	s_getreg_b32 s6, hwreg(HW_REG_XCC_ID, 0, 4)
	s_waitcnt vmcnt(0)
	s_waitcnt lgkmcnt(0)
	s_barrier
	v_readfirstlane_b32 s5, v3
	v_readfirstlane_b32 s4, v2
	s_and_saveexec_b64 s[2:3], s[66:67]
	s_cbranch_execz .LBB0_139
	v_mov_b32_e32 v0, s87
	s_waitcnt vmcnt(0) expcnt(0) lgkmcnt(0)
	ds_read_b32 v3, v0
	v_mov_b32_e32 v0, s90
	ds_read_b32 v2, v0
	s_and_b32 s48, s6, 15
	s_waitcnt lgkmcnt(1)
	v_cmp_ne_u32_e32 vcc, 0, v3
	s_cbranch_vccnz .LBB0_103
	s_add_u32 s6, s4, 0x1200
	s_addc_u32 s7, s5, 0
	s_add_u32 s8, s4, 0x1400
	s_addc_u32 s9, s5, 0
	s_add_u32 s10, s4, 0x1500
	s_addc_u32 s11, s5, 0
	s_add_u32 s12, s4, 0x1600
	s_addc_u32 s13, s5, 0
	s_add_u32 s14, s4, 0x1700
	s_addc_u32 s15, s5, 0
	s_add_u32 s16, s4, 0x1800
	s_addc_u32 s17, s5, 0
	s_add_u32 s18, s4, 0x1900
	s_addc_u32 s19, s5, 0
	s_add_u32 s20, s4, 0x1a00
	s_addc_u32 s21, s5, 0
	s_add_u32 s22, s4, 0x1b00
	s_addc_u32 s23, s5, 0
	s_add_u32 s24, s4, 0x1c00
	s_addc_u32 s25, s5, 0
	s_add_u32 s26, s4, 0x1d00
	s_addc_u32 s27, s5, 0
	s_mov_b32 s50, s28
	s_add_u32 s28, s4, 0x1e00
	s_addc_u32 s29, s5, 0
	s_add_u32 s30, s4, 0x1f00
	s_addc_u32 s31, s5, 0
	s_add_u32 s34, s4, 0x2000
	s_addc_u32 s35, s5, 0
	s_add_u32 s36, s4, 0x2100
	s_addc_u32 s37, s5, 0
	s_add_u32 s38, s4, 0x2200
	s_addc_u32 s39, s5, 0
	s_add_u32 s40, s4, 0x2300
	s_addc_u32 s41, s5, 0
	s_mov_b32 s49, 1
	s_branch .LBB0_90
